# final_rows: all 16 per-row loads (mix, g_post, gate, x) issued up front with counted vmcnt, on top of v20
# speedup vs baseline: 1.0042x; 1.0042x over previous
; __device__ __forceinline__ void ph_final_rows(int pb) {
;     ...
;     for (int m = gw; m < TG; m += NGW) { const int t = pb + m, b = t >> 12;
;         float sv = lane < 16 ? SSQ_FF[lane * TT + t] : 0.f; sv += __shfl_xor(sv, 1); sv += __shfl_xor(sv, 2); sv += __shfl_xor(sv, 4); sv += __shfl_xor(sv, 8); sv = __shfl(sv, 0);
;         const float rs = rsqrtf(sv * (1.f / 1024.f) + EPS); const float* gate2 = MOD + b * 6144 + 5120;
; #pragma unroll
;         for (int j = 0; j < 4; ++j) { const int c0 = 4 * lane + 256 * j; const u32x2 w = *(const u32x2*)(FF + (size_t)m * 1024 + c0);
;             f32x4 f = {bflo(w.x), bfhi(w.x), bflo(w.y), bfhi(w.y)}; const f32x4 g = *(const f32x4*)(g_post_mlp + c0), ga = *(const f32x4*)(gate2 + c0);
;             f32x4* op = (f32x4*)(out + (size_t)t * 1024 + c0); *op = *op + ga * (f * rs * g); } }
.LBB0_1443:
	s_or_b64 exec, exec, s[0:1]
	s_add_i32 s0, s2, 0xc000
	s_ashr_i32 s1, s0, 12
	s_mul_i32 s12, s1, 0x1800
	s_ashr_i32 s13, s12, 31
	s_lshl_b64 s[12:13], s[12:13], 2
	s_add_u32 s1, s6, s12
	s_addc_u32 s5, s7, s13
	s_add_u32 s12, s1, 0x105000
	global_load_dwordx2 v[34:35], v[4:5], off
	s_addc_u32 s13, s5, 0
	s_ashr_i32 s1, s0, 31
	s_lshl_b64 s[0:1], s[0:1], 12
	v_lshl_add_u64 v[36:37], v[2:3], 0, s[0:1]
	global_load_dwordx4 v[18:21], v[0:1], off
	global_load_dwordx4 v[22:25], v13, s[12:13]
	global_load_dwordx4 v[26:29], v[36:37], off
	global_load_dwordx4 v[82:85], v[36:37], off offset:1024
	global_load_dwordx2 v[44:45], v[4:5], off offset:512
	global_load_dwordx4 v[48:51], v[0:1], off offset:1024
	global_load_dwordx4 v[52:55], v14, s[12:13]
	global_load_dwordx2 v[46:47], v[4:5], off offset:1024
	global_load_dwordx4 v[56:59], v[0:1], off offset:2048
	global_load_dwordx4 v[60:63], v15, s[12:13]
	global_load_dwordx4 v[64:67], v[36:37], off offset:2048
	global_load_dwordx4 v[68:71], v[36:37], off offset:3072
	global_load_dwordx2 v[72:73], v[4:5], off offset:1536
	global_load_dwordx4 v[74:77], v[0:1], off offset:3072
	global_load_dwordx4 v[78:81], v16, s[12:13]
	s_waitcnt vmcnt(16)
	ds_bpermute_b32 v30, v6, v17
	s_add_i32 s2, s2, s4
	s_cmpk_lt_i32 s2, 0x4000
	s_waitcnt lgkmcnt(0)
	v_add_f32_e32 v17, v17, v30
	ds_bpermute_b32 v30, v7, v17
	s_waitcnt lgkmcnt(0)
	v_add_f32_e32 v17, v17, v30
	ds_bpermute_b32 v30, v8, v17
	s_waitcnt lgkmcnt(0)
	v_add_f32_e32 v17, v17, v30
	ds_bpermute_b32 v30, v9, v17
	s_waitcnt lgkmcnt(0)
	v_add_f32_e32 v17, v17, v30
	ds_bpermute_b32 v17, v10, v17
	s_waitcnt lgkmcnt(0)
	v_fmamk_f32 v17, v17, 0x3a800000, v12
	v_mul_f32_e32 v30, 0x4b800000, v17
	v_cmp_gt_f32_e64 s[0:1], s3, v17
	s_waitcnt vmcnt(15)
	v_lshlrev_b32_e32 v40, 16, v34
	v_cndmask_b32_e64 v17, v17, v30, s[0:1]
	v_rsq_f32_e32 v17, v17
	v_and_b32_e32 v41, 0xffff0000, v34
	v_lshlrev_b32_e32 v34, 16, v35
	v_and_b32_e32 v35, 0xffff0000, v35
	v_mul_f32_e32 v38, 0x45800000, v17
	v_cndmask_b32_e64 v38, v17, v38, s[0:1]
	v_pk_mul_f32 v[34:35], v[38:39], v[34:35] op_sel_hi:[0,1]
	v_pk_mul_f32 v[40:41], v[38:39], v[40:41] op_sel_hi:[0,1]
	s_waitcnt vmcnt(14)
	v_pk_mul_f32 v[18:19], v[18:19], v[40:41]
	v_pk_mul_f32 v[20:21], v[20:21], v[34:35]
	s_waitcnt vmcnt(12)
	v_pk_fma_f32 v[20:21], v[24:25], v[20:21], v[28:29]
	v_pk_fma_f32 v[18:19], v[22:23], v[18:19], v[26:27]
	global_store_dwordx4 v[36:37], v[18:21], off
	s_waitcnt vmcnt(11)
	v_lshlrev_b32_e32 v28, 16, v44
	v_and_b32_e32 v29, 0xffff0000, v44
	v_lshlrev_b32_e32 v26, 16, v45
	v_and_b32_e32 v27, 0xffff0000, v45
	v_pk_mul_f32 v[26:27], v[38:39], v[26:27] op_sel_hi:[0,1]
	v_pk_mul_f32 v[28:29], v[38:39], v[28:29] op_sel_hi:[0,1]
	s_waitcnt vmcnt(10)
	v_pk_mul_f32 v[18:19], v[48:49], v[28:29]
	v_pk_mul_f32 v[20:21], v[50:51], v[26:27]
	s_waitcnt vmcnt(9)
	v_pk_fma_f32 v[18:19], v[52:53], v[18:19], v[82:83]
	v_pk_fma_f32 v[20:21], v[54:55], v[20:21], v[84:85]
	global_store_dwordx4 v[36:37], v[18:21], off offset:1024
	s_waitcnt vmcnt(9)
	v_lshlrev_b32_e32 v40, 16, v46
	v_and_b32_e32 v41, 0xffff0000, v46
	v_lshlrev_b32_e32 v34, 16, v47
	v_and_b32_e32 v35, 0xffff0000, v47
	v_pk_mul_f32 v[34:35], v[38:39], v[34:35] op_sel_hi:[0,1]
	v_pk_mul_f32 v[40:41], v[38:39], v[40:41] op_sel_hi:[0,1]
	s_waitcnt vmcnt(8)
	v_pk_mul_f32 v[18:19], v[56:57], v[40:41]
	v_pk_mul_f32 v[20:21], v[58:59], v[34:35]
	s_waitcnt vmcnt(6)
	v_pk_fma_f32 v[18:19], v[60:61], v[18:19], v[64:65]
	v_pk_fma_f32 v[20:21], v[62:63], v[20:21], v[66:67]
	global_store_dwordx4 v[36:37], v[18:21], off offset:2048
	v_lshl_add_u64 v[4:5], v[4:5], 0, s[10:11]
	s_waitcnt vmcnt(5)
	v_lshlrev_b32_e32 v28, 16, v72
	v_and_b32_e32 v29, 0xffff0000, v72
	v_lshlrev_b32_e32 v26, 16, v73
	v_and_b32_e32 v27, 0xffff0000, v73
	v_pk_mul_f32 v[26:27], v[38:39], v[26:27] op_sel_hi:[0,1]
	v_pk_mul_f32 v[28:29], v[38:39], v[28:29] op_sel_hi:[0,1]
	s_waitcnt vmcnt(4)
	v_pk_mul_f32 v[18:19], v[74:75], v[28:29]
	v_pk_mul_f32 v[20:21], v[76:77], v[26:27]
	s_waitcnt vmcnt(3)
	v_pk_fma_f32 v[18:19], v[78:79], v[18:19], v[68:69]
	v_pk_fma_f32 v[20:21], v[80:81], v[20:21], v[70:71]
	global_store_dwordx4 v[36:37], v[18:21], off offset:3072
	s_cbranch_scc0 .LBB0_1446
